# FFN-down K=4096 k-loops: steady-state copy of the loop body with counted vmcnt waits (15/14) instead of hipcc's pessimistic vmcnt(1)/vmcnt(0) merged across the conditional prefetch paths; first and la
# speedup vs baseline: 1.0058x; 1.0058x over previous
; template <class AL, class BL>
; DI void gemm_core(AL al, BL bl, int m0, int n0, int K, char* smem, f32x16 (&acc)[2][2]) {
;     ...
;   for (int kt = 0; kt < nk; kt += 2) {
;     G_TILE(0, x, true, (kt + 3 < nk), kt + 3);
;     __syncthreads();
;     G_TILE(1, y, (kt + 2 < nk), (kt + 4 < nk), kt + 4);
;     __syncthreads();
;   }
.LBB0_1043:
	s_add_i32 s1, s1, 2
	v_lshl_add_u64 v[164:165], v[164:165], 0, s[36:37]
	v_lshl_add_u64 v[162:163], v[162:163], 0, s[36:37]
	v_lshl_add_u64 v[166:167], v[166:167], 0, s[36:37]
	v_lshl_add_u64 v[168:169], v[168:169], 0, s[36:37]
	v_lshl_add_u64 v[170:171], v[170:171], 0, s[36:37]
	v_lshl_add_u64 v[172:173], v[172:173], 0, s[36:37]
	v_lshl_add_u64 v[174:175], v[174:175], 0, s[36:37]
	s_andn2_b64 vcc, exec, s[2:3]
	v_lshl_add_u64 v[176:177], v[176:177], 0, s[36:37]
	s_waitcnt lgkmcnt(0)
	s_barrier
	s_cbranch_vccz .LBB0_1034
	s_cmp_lt_u32 s1, 59
	s_cbranch_scc1 .Lfd0_hdr

; #define G_LOAD(S, kt_) do { G_LD1(S##a0, S##b0, 0, kt_); G_LD1(S##a1, S##b1, 1, kt_); G_LD1(S##a2, S##b2, 2, kt_); G_LD1(S##a3, S##b3, 3, kt_); } while (0)
; #define G_STORE(S, buf_) do { G_ST1(S##a0, S##b0, 0, buf_); G_ST1(S##a1, S##b1, 1, buf_); G_ST1(S##a2, S##b2, 2, buf_); G_ST1(S##a3, S##b3, 3, buf_); } while (0)
; template <class AL, class BL>
; DI void gemm_core(AL al, BL bl, int m0, int n0, int K, char* smem, f32x16 (&acc)[2][2]) {
;     ...
;   G_LOAD(x, 0);
;   G_STORE(x, 0);
;   G_LOAD(x, 1);
;   G_LOAD(y, (nk > 2) ? 2 : 1);
;   __syncthreads();
;   for (int kt = 0; kt < nk; kt += 2) {
;     G_TILE(0, x, true, (kt + 3 < nk), kt + 3);
;     __syncthreads();
;     G_TILE(1, y, (kt + 2 < nk), (kt + 4 < nk), kt + 4);
;     __syncthreads();
.Lfd0_hdr:
	ds_read_b128 v[132:135], v160
	ds_read_b128 v[144:147], v159 offset:36864
	ds_read_b128 v[136:139], v160 offset:32
	ds_read_b128 v[140:143], v159 offset:36896
	ds_read_b128 v[148:151], v159 offset:41472
	ds_read_b128 v[128:131], v159 offset:41504
	s_cmp_lt_u32 s1, 61
	s_waitcnt lgkmcnt(4)
	v_mfma_f32_32x32x16_bf16 v[48:63], v[132:135], v[144:147], v[48:63]
	s_cselect_b64 s[2:3], -1, 0
	s_cmp_gt_u32 s1, 60
	v_lshl_add_u64 v[188:189], v[164:165], 0, v[156:157]
	v_lshl_add_u64 v[184:185], v[162:163], 0, v[156:157]
	s_waitcnt lgkmcnt(1)
	v_mfma_f32_32x32x16_bf16 v[32:47], v[132:135], v[148:151], v[32:47]
	ds_read_b128 v[152:155], v160 offset:4608
	ds_read_b128 v[132:135], v160 offset:4640
	s_waitcnt vmcnt(15)
	ds_write_b128 v158, v[64:67] offset:18432
	s_waitcnt vmcnt(14)
	ds_write_b128 v158, v[72:75] offset:55296
	s_waitcnt lgkmcnt(3)
	v_mfma_f32_32x32x16_bf16 v[16:31], v[152:155], v[144:147], v[16:31]
	v_mfma_f32_32x32x16_bf16 v[0:15], v[152:155], v[148:151], v[0:15]
	s_cbranch_scc1 .Lfd0_1046
	v_add_co_u32_e32 v64, vcc, 0x4c00000, v188
	s_nop 1
	v_addc_co_u32_e32 v65, vcc, 0, v189, vcc
	v_add_co_u32_e32 v72, vcc, 0xe400000, v184
	global_load_dwordx4 v[64:67], v[64:65], off offset:384
	s_nop 0
	v_addc_co_u32_e32 v73, vcc, 0, v185, vcc
	global_load_dwordx4 v[72:75], v[72:73], off offset:384
.Lfd0_1046:
	v_mfma_f32_32x32x16_bf16 v[48:63], v[136:139], v[140:143], v[48:63]
	s_andn2_b64 vcc, exec, s[2:3]
	v_lshl_add_u64 v[186:187], v[166:167], 0, v[156:157]
	v_lshl_add_u64 v[180:181], v[168:169], 0, v[156:157]
	v_mfma_f32_32x32x16_bf16 v[32:47], v[136:139], v[128:131], v[32:47]
	ds_read_b128 v[152:155], v160 offset:64
	ds_read_b128 v[136:139], v160 offset:4672
	ds_read_b128 v[148:151], v159 offset:36928
	ds_read_b128 v[144:147], v159 offset:41536
	s_waitcnt vmcnt(15)
	ds_write_b128 v158, v[84:87] offset:23040
	s_waitcnt vmcnt(14)
	ds_write_b128 v158, v[80:83] offset:59904
	s_waitcnt lgkmcnt(8)
	v_mfma_f32_32x32x16_bf16 v[16:31], v[132:135], v[140:143], v[16:31]
	v_cndmask_b32_e64 v140, 0, 1, s[2:3]
	v_cmp_ne_u32_e64 s[12:13], 1, v140
	v_mfma_f32_32x32x16_bf16 v[0:15], v[132:135], v[128:131], v[0:15]
	s_cbranch_vccnz .Lfd0_1048
	v_add_co_u32_e32 v80, vcc, 0x4c00000, v186
	s_nop 1
	v_addc_co_u32_e32 v81, vcc, 0, v187, vcc
	global_load_dwordx4 v[84:87], v[80:81], off offset:384
	v_add_co_u32_e32 v80, vcc, 0xe400000, v180
	s_nop 1
	v_addc_co_u32_e32 v81, vcc, 0, v181, vcc
	global_load_dwordx4 v[80:83], v[80:81], off offset:384
.Lfd0_1048:
	s_waitcnt lgkmcnt(3)
	v_mfma_f32_32x32x16_bf16 v[48:63], v[152:155], v[148:151], v[48:63]
	ds_read_b128 v[140:143], v160 offset:96
	ds_read_b128 v[128:131], v160 offset:4704
	s_and_b64 vcc, exec, s[12:13]
	v_lshl_add_u64 v[182:183], v[170:171], 0, v[156:157]
	s_waitcnt lgkmcnt(4)
	v_mfma_f32_32x32x16_bf16 v[32:47], v[152:155], v[144:147], v[32:47]
	v_lshl_add_u64 v[154:155], v[172:173], 0, v[156:157]
	v_mfma_f32_32x32x16_bf16 v[16:31], v[136:139], v[148:151], v[16:31]
	ds_read_b128 v[148:151], v159 offset:36960
	ds_read_b128 v[132:135], v159 offset:41568
	s_waitcnt vmcnt(15)
	ds_write_b128 v158, v[88:91] offset:27648
	s_waitcnt vmcnt(14)
	ds_write_b128 v158, v[96:99] offset:64512
	v_mfma_f32_32x32x16_bf16 v[0:15], v[136:139], v[144:147], v[0:15]
	s_cbranch_vccnz .Lfd0_1050
	v_add_co_u32_e32 v88, vcc, 0x4c00000, v182
	s_nop 1
	v_addc_co_u32_e32 v89, vcc, 0, v183, vcc
	v_add_co_u32_e32 v96, vcc, 0xe400000, v154
	global_load_dwordx4 v[88:91], v[88:89], off offset:384
	s_nop 0
	v_addc_co_u32_e32 v97, vcc, 0, v155, vcc
	global_load_dwordx4 v[96:99], v[96:97], off offset:384
.Lfd0_1050:
	s_waitcnt lgkmcnt(3)
	v_mfma_f32_32x32x16_bf16 v[48:63], v[140:143], v[148:151], v[48:63]
	s_and_b64 vcc, exec, s[12:13]
	v_lshl_add_u64 v[178:179], v[174:175], 0, v[156:157]
	v_lshl_add_u64 v[152:153], v[176:177], 0, v[156:157]
	s_waitcnt vmcnt(15)
	ds_write_b128 v158, v[100:103] offset:32256
	s_waitcnt vmcnt(14)
	ds_write_b128 v161, v[112:115] offset:32256
	s_waitcnt lgkmcnt(4)
	v_mfma_f32_32x32x16_bf16 v[32:47], v[140:143], v[132:135], v[32:47]
	v_mfma_f32_32x32x16_bf16 v[16:31], v[128:131], v[148:151], v[16:31]
	v_mfma_f32_32x32x16_bf16 v[0:15], v[128:131], v[132:135], v[0:15]
	s_cbranch_vccnz .Lfd0_1052
	v_add_co_u32_e32 v100, vcc, 0x4c00000, v178
	s_nop 1
	v_addc_co_u32_e32 v101, vcc, 0, v179, vcc
	v_add_co_u32_e32 v112, vcc, 0xe400000, v152
	global_load_dwordx4 v[100:103], v[100:101], off offset:384
	s_nop 0
	v_addc_co_u32_e32 v113, vcc, 0, v153, vcc
	global_load_dwordx4 v[112:115], v[112:113], off offset:384
.Lfd0_1052:
	s_waitcnt lgkmcnt(0)
	s_barrier
	ds_read_b128 v[132:135], v160 offset:18432
	ds_read_b128 v[144:147], v159 offset:55296
	ds_read_b128 v[140:143], v160 offset:18464
	ds_read_b128 v[136:139], v159 offset:55328
	ds_read_b128 v[148:151], v159 offset:59904
	ds_read_b128 v[128:131], v159 offset:59936
	s_waitcnt lgkmcnt(4)
	v_mfma_f32_32x32x16_bf16 v[48:63], v[132:135], v[144:147], v[48:63]
	s_cmp_lt_u32 s1, 62
	s_cselect_b64 s[14:15], -1, 0
	s_cmp_gt_u32 s1, 61
	s_cselect_b64 s[2:3], -1, 0
	s_and_b64 vcc, exec, s[2:3]
	s_waitcnt lgkmcnt(1)
	v_mfma_f32_32x32x16_bf16 v[32:47], v[132:135], v[148:151], v[32:47]
	ds_read_b128 v[190:193], v160 offset:23040
	ds_read_b128 v[132:135], v160 offset:23072
	s_waitcnt lgkmcnt(1)
	v_mfma_f32_32x32x16_bf16 v[16:31], v[190:193], v[144:147], v[16:31]
	v_mfma_f32_32x32x16_bf16 v[0:15], v[190:193], v[148:151], v[0:15]
	s_cbranch_vccnz .Lfd0_1054
	s_waitcnt vmcnt(15)
	ds_write_b128 v158, v[68:71]
	s_waitcnt vmcnt(14)
	ds_write_b128 v158, v[76:79] offset:36864

.Lfd0_1056:
	v_mfma_f32_32x32x16_bf16 v[48:63], v[140:143], v[136:139], v[48:63]
	v_cndmask_b32_e64 v184, 0, 1, s[14:15]
	v_cmp_ne_u32_e64 s[12:13], 1, v184
	s_andn2_b64 vcc, exec, s[14:15]
	v_mfma_f32_32x32x16_bf16 v[32:47], v[140:143], v[128:131], v[32:47]
	s_waitcnt lgkmcnt(0)
	v_mfma_f32_32x32x16_bf16 v[16:31], v[132:135], v[136:139], v[16:31]
	ds_read_b128 v[144:147], v160 offset:18496
	ds_read_b128 v[136:139], v160 offset:23104
	ds_read_b128 v[148:151], v159 offset:55360
	ds_read_b128 v[140:143], v159 offset:59968
	v_mfma_f32_32x32x16_bf16 v[0:15], v[132:135], v[128:131], v[0:15]
	s_cbranch_vccnz .Lfd0_1058
	s_waitcnt vmcnt(15)
	ds_write_b128 v158, v[104:107] offset:4608
	s_waitcnt vmcnt(14)
	ds_write_b128 v158, v[92:95] offset:41472

.Lfd0_1060:
	s_waitcnt lgkmcnt(1)
	v_mfma_f32_32x32x16_bf16 v[48:63], v[144:147], v[148:151], v[48:63]
	s_and_b64 vcc, exec, s[12:13]
	s_waitcnt lgkmcnt(0)
	v_mfma_f32_32x32x16_bf16 v[32:47], v[144:147], v[140:143], v[32:47]
	v_mfma_f32_32x32x16_bf16 v[16:31], v[136:139], v[148:151], v[16:31]
	ds_read_b128 v[144:147], v160 offset:18528
	ds_read_b128 v[128:131], v160 offset:23136
	ds_read_b128 v[148:151], v159 offset:55392
	ds_read_b128 v[132:135], v159 offset:60000
	v_mfma_f32_32x32x16_bf16 v[0:15], v[136:139], v[140:143], v[0:15]
	s_cbranch_vccnz .Lfd0_1062
	s_waitcnt vmcnt(15)
	ds_write_b128 v158, v[116:119] offset:9216
	s_waitcnt vmcnt(14)
	ds_write_b128 v158, v[108:111] offset:46080

.Lfd0_1064:
	s_waitcnt lgkmcnt(1)
	v_mfma_f32_32x32x16_bf16 v[48:63], v[144:147], v[148:151], v[48:63]
	s_and_b64 vcc, exec, s[12:13]
	s_waitcnt lgkmcnt(0)
	v_mfma_f32_32x32x16_bf16 v[32:47], v[144:147], v[132:135], v[32:47]
	v_mfma_f32_32x32x16_bf16 v[16:31], v[128:131], v[148:151], v[16:31]
	v_mfma_f32_32x32x16_bf16 v[0:15], v[128:131], v[132:135], v[0:15]
	s_cbranch_vccnz .Lfd0_1066
	s_waitcnt vmcnt(15)
	ds_write_b128 v158, v[124:127] offset:13824
	s_waitcnt vmcnt(14)
	ds_write_b128 v158, v[120:123] offset:50688

; template <class AL, class BL>
; DI void gemm_core(AL al, BL bl, int m0, int n0, int K, char* smem, f32x16 (&acc)[2][2]) {
;     ...
;   for (int kt = 0; kt < nk; kt += 2) {
;     G_TILE(0, x, true, (kt + 3 < nk), kt + 3);
;     __syncthreads();
;     G_TILE(1, y, (kt + 2 < nk), (kt + 4 < nk), kt + 4);
;     __syncthreads();
;   }
.Lfd0_latch:
	s_add_i32 s1, s1, 2
	v_lshl_add_u64 v[164:165], v[164:165], 0, s[36:37]
	v_lshl_add_u64 v[162:163], v[162:163], 0, s[36:37]
	v_lshl_add_u64 v[166:167], v[166:167], 0, s[36:37]
	v_lshl_add_u64 v[168:169], v[168:169], 0, s[36:37]
	v_lshl_add_u64 v[170:171], v[170:171], 0, s[36:37]
	v_lshl_add_u64 v[172:173], v[172:173], 0, s[36:37]
	v_lshl_add_u64 v[174:175], v[174:175], 0, s[36:37]
	s_andn2_b64 vcc, exec, s[2:3]
	v_lshl_add_u64 v[176:177], v[176:177], 0, s[36:37]
	s_waitcnt lgkmcnt(0)
	s_barrier
	s_cbranch_vccz .LBB0_1034
	s_cmp_lt_u32 s1, 59
	s_cbranch_scc1 .Lfd0_hdr
	s_branch .LBB0_1044

; template <class AL, class BL>
; DI void gemm_core(AL al, BL bl, int m0, int n0, int K, char* smem, f32x16 (&acc)[2][2]) {
;     ...
;   for (int kt = 0; kt < nk; kt += 2) {
;     G_TILE(0, x, true, (kt + 3 < nk), kt + 3);
;     __syncthreads();
;     G_TILE(1, y, (kt + 2 < nk), (kt + 4 < nk), kt + 4);
;     __syncthreads();
;   }
.LBB0_1739:
	s_add_i32 s1, s1, 2
	v_lshl_add_u64 v[164:165], v[164:165], 0, s[28:29]
	v_lshl_add_u64 v[162:163], v[162:163], 0, s[28:29]
	v_lshl_add_u64 v[166:167], v[166:167], 0, s[28:29]
	v_lshl_add_u64 v[168:169], v[168:169], 0, s[28:29]
	v_lshl_add_u64 v[170:171], v[170:171], 0, s[28:29]
	v_lshl_add_u64 v[172:173], v[172:173], 0, s[28:29]
	v_lshl_add_u64 v[174:175], v[174:175], 0, s[28:29]
	s_andn2_b64 vcc, exec, s[2:3]
	v_lshl_add_u64 v[176:177], v[176:177], 0, s[28:29]
	s_waitcnt lgkmcnt(0)
	s_barrier
	s_cbranch_vccz .LBB0_1730
	s_cmp_lt_u32 s1, 59
	s_cbranch_scc1 .Lfd1_hdr

; #define G_LOAD(S, kt_) do { G_LD1(S##a0, S##b0, 0, kt_); G_LD1(S##a1, S##b1, 1, kt_); G_LD1(S##a2, S##b2, 2, kt_); G_LD1(S##a3, S##b3, 3, kt_); } while (0)
; #define G_STORE(S, buf_) do { G_ST1(S##a0, S##b0, 0, buf_); G_ST1(S##a1, S##b1, 1, buf_); G_ST1(S##a2, S##b2, 2, buf_); G_ST1(S##a3, S##b3, 3, buf_); } while (0)
; template <class AL, class BL>
; DI void gemm_core(AL al, BL bl, int m0, int n0, int K, char* smem, f32x16 (&acc)[2][2]) {
;     ...
;   G_LOAD(x, 0);
;   G_STORE(x, 0);
;   G_LOAD(x, 1);
;   G_LOAD(y, (nk > 2) ? 2 : 1);
;   __syncthreads();
;   for (int kt = 0; kt < nk; kt += 2) {
;     G_TILE(0, x, true, (kt + 3 < nk), kt + 3);
;     __syncthreads();
;     G_TILE(1, y, (kt + 2 < nk), (kt + 4 < nk), kt + 4);
;     __syncthreads();
.Lfd1_hdr:
	ds_read_b128 v[132:135], v160
	ds_read_b128 v[144:147], v159 offset:36864
	ds_read_b128 v[136:139], v160 offset:32
	ds_read_b128 v[140:143], v159 offset:36896
	ds_read_b128 v[148:151], v159 offset:41472
	ds_read_b128 v[128:131], v159 offset:41504
	s_cmp_lt_u32 s1, 61
	s_waitcnt lgkmcnt(4)
	v_mfma_f32_32x32x16_bf16 v[48:63], v[132:135], v[144:147], v[48:63]
	s_cselect_b64 s[2:3], -1, 0
	s_cmp_gt_u32 s1, 60
	v_lshl_add_u64 v[188:189], v[164:165], 0, v[156:157]
	v_lshl_add_u64 v[184:185], v[162:163], 0, v[156:157]
	s_waitcnt lgkmcnt(1)
	v_mfma_f32_32x32x16_bf16 v[32:47], v[132:135], v[148:151], v[32:47]
	ds_read_b128 v[152:155], v160 offset:4608
	ds_read_b128 v[132:135], v160 offset:4640
	s_waitcnt vmcnt(15)
	ds_write_b128 v158, v[64:67] offset:18432
	s_waitcnt vmcnt(14)
	ds_write_b128 v158, v[72:75] offset:55296
	s_waitcnt lgkmcnt(3)
	v_mfma_f32_32x32x16_bf16 v[16:31], v[152:155], v[144:147], v[16:31]
	v_mfma_f32_32x32x16_bf16 v[0:15], v[152:155], v[148:151], v[0:15]
	s_cbranch_scc1 .Lfd1_1742
	v_add_co_u32_e32 v64, vcc, 0x8000000, v188
	s_nop 1
	v_addc_co_u32_e32 v65, vcc, 0, v189, vcc
	v_add_co_u32_e32 v72, vcc, 0x7800000, v184
	global_load_dwordx4 v[64:67], v[64:65], off offset:384
	s_nop 0
	v_addc_co_u32_e32 v73, vcc, 0, v185, vcc
	global_load_dwordx4 v[72:75], v[72:73], off offset:384
.Lfd1_1742:
	v_mfma_f32_32x32x16_bf16 v[48:63], v[136:139], v[140:143], v[48:63]
	s_andn2_b64 vcc, exec, s[2:3]
	v_lshl_add_u64 v[186:187], v[166:167], 0, v[156:157]
	v_lshl_add_u64 v[180:181], v[168:169], 0, v[156:157]
	v_mfma_f32_32x32x16_bf16 v[32:47], v[136:139], v[128:131], v[32:47]
	ds_read_b128 v[152:155], v160 offset:64
	ds_read_b128 v[136:139], v160 offset:4672
	ds_read_b128 v[148:151], v159 offset:36928
	ds_read_b128 v[144:147], v159 offset:41536
	s_waitcnt vmcnt(15)
	ds_write_b128 v158, v[96:99] offset:23040
	s_waitcnt vmcnt(14)
	ds_write_b128 v158, v[80:83] offset:59904
	s_waitcnt lgkmcnt(8)
	v_mfma_f32_32x32x16_bf16 v[16:31], v[132:135], v[140:143], v[16:31]
	v_cndmask_b32_e64 v140, 0, 1, s[2:3]
	v_cmp_ne_u32_e64 s[6:7], 1, v140
	v_mfma_f32_32x32x16_bf16 v[0:15], v[132:135], v[128:131], v[0:15]
	s_cbranch_vccnz .Lfd1_1744
	v_add_co_u32_e32 v80, vcc, 0x8000000, v186
	s_nop 1
	v_addc_co_u32_e32 v81, vcc, 0, v187, vcc
	global_load_dwordx4 v[96:99], v[80:81], off offset:384
	v_add_co_u32_e32 v80, vcc, 0x7800000, v180
	s_nop 1
	v_addc_co_u32_e32 v81, vcc, 0, v181, vcc
	global_load_dwordx4 v[80:83], v[80:81], off offset:384
.Lfd1_1744:
	s_waitcnt lgkmcnt(3)
	v_mfma_f32_32x32x16_bf16 v[48:63], v[152:155], v[148:151], v[48:63]
	ds_read_b128 v[140:143], v160 offset:96
	ds_read_b128 v[128:131], v160 offset:4704
	s_and_b64 vcc, exec, s[6:7]
	v_lshl_add_u64 v[182:183], v[170:171], 0, v[156:157]
	s_waitcnt lgkmcnt(4)
	v_mfma_f32_32x32x16_bf16 v[32:47], v[152:155], v[144:147], v[32:47]
	v_lshl_add_u64 v[154:155], v[172:173], 0, v[156:157]
	v_mfma_f32_32x32x16_bf16 v[16:31], v[136:139], v[148:151], v[16:31]
	ds_read_b128 v[148:151], v159 offset:36960
	ds_read_b128 v[132:135], v159 offset:41568
	s_waitcnt vmcnt(15)
	ds_write_b128 v158, v[104:107] offset:27648
	s_waitcnt vmcnt(14)
	ds_write_b128 v158, v[88:91] offset:64512
	v_mfma_f32_32x32x16_bf16 v[0:15], v[136:139], v[144:147], v[0:15]
	s_cbranch_vccnz .Lfd1_1746
	v_add_co_u32_e32 v88, vcc, 0x8000000, v182
	s_nop 1
	v_addc_co_u32_e32 v89, vcc, 0, v183, vcc
	global_load_dwordx4 v[104:107], v[88:89], off offset:384
	v_add_co_u32_e32 v88, vcc, 0x7800000, v154
	s_nop 1
	v_addc_co_u32_e32 v89, vcc, 0, v155, vcc
	global_load_dwordx4 v[88:91], v[88:89], off offset:384
.Lfd1_1746:
	s_waitcnt lgkmcnt(3)
	v_mfma_f32_32x32x16_bf16 v[48:63], v[140:143], v[148:151], v[48:63]
	s_and_b64 vcc, exec, s[6:7]
	v_lshl_add_u64 v[178:179], v[174:175], 0, v[156:157]
	v_lshl_add_u64 v[152:153], v[176:177], 0, v[156:157]
	s_waitcnt vmcnt(15)
	ds_write_b128 v158, v[112:115] offset:32256
	s_waitcnt vmcnt(14)
	ds_write_b128 v161, v[100:103] offset:32256
	s_waitcnt lgkmcnt(4)
	v_mfma_f32_32x32x16_bf16 v[32:47], v[140:143], v[132:135], v[32:47]
	v_mfma_f32_32x32x16_bf16 v[16:31], v[128:131], v[148:151], v[16:31]
	v_mfma_f32_32x32x16_bf16 v[0:15], v[128:131], v[132:135], v[0:15]
	s_cbranch_vccnz .Lfd1_1748
	v_add_co_u32_e32 v100, vcc, 0x8000000, v178
	s_nop 1
	v_addc_co_u32_e32 v101, vcc, 0, v179, vcc
	global_load_dwordx4 v[112:115], v[100:101], off offset:384
	v_add_co_u32_e32 v100, vcc, 0x7800000, v152
	s_nop 1
	v_addc_co_u32_e32 v101, vcc, 0, v153, vcc
	global_load_dwordx4 v[100:103], v[100:101], off offset:384
.Lfd1_1748:
	s_waitcnt lgkmcnt(0)
	s_barrier
	ds_read_b128 v[132:135], v160 offset:18432
	ds_read_b128 v[144:147], v159 offset:55296
	ds_read_b128 v[140:143], v160 offset:18464
	ds_read_b128 v[136:139], v159 offset:55328
	ds_read_b128 v[148:151], v159 offset:59904
	ds_read_b128 v[128:131], v159 offset:59936
	s_waitcnt lgkmcnt(4)
	v_mfma_f32_32x32x16_bf16 v[48:63], v[132:135], v[144:147], v[48:63]
	s_cmp_lt_u32 s1, 62
	s_cselect_b64 s[8:9], -1, 0
	s_cmp_gt_u32 s1, 61
	s_cselect_b64 s[2:3], -1, 0
	s_and_b64 vcc, exec, s[2:3]
	s_waitcnt lgkmcnt(1)
	v_mfma_f32_32x32x16_bf16 v[32:47], v[132:135], v[148:151], v[32:47]
	ds_read_b128 v[190:193], v160 offset:23040
	ds_read_b128 v[132:135], v160 offset:23072
	s_waitcnt lgkmcnt(1)
	v_mfma_f32_32x32x16_bf16 v[16:31], v[190:193], v[144:147], v[16:31]
	v_mfma_f32_32x32x16_bf16 v[0:15], v[190:193], v[148:151], v[0:15]
	s_cbranch_vccnz .Lfd1_1750
	s_waitcnt vmcnt(15)
	ds_write_b128 v158, v[68:71]
	s_waitcnt vmcnt(14)
	ds_write_b128 v158, v[76:79] offset:36864

.Lfd1_1752:
	v_mfma_f32_32x32x16_bf16 v[48:63], v[140:143], v[136:139], v[48:63]
	v_cndmask_b32_e64 v184, 0, 1, s[8:9]
	v_cmp_ne_u32_e64 s[6:7], 1, v184
	s_andn2_b64 vcc, exec, s[8:9]
	v_mfma_f32_32x32x16_bf16 v[32:47], v[140:143], v[128:131], v[32:47]
	s_waitcnt lgkmcnt(0)
	v_mfma_f32_32x32x16_bf16 v[16:31], v[132:135], v[136:139], v[16:31]
	ds_read_b128 v[144:147], v160 offset:18496
	ds_read_b128 v[136:139], v160 offset:23104
	ds_read_b128 v[148:151], v159 offset:55360
	ds_read_b128 v[140:143], v159 offset:59968
	v_mfma_f32_32x32x16_bf16 v[0:15], v[132:135], v[128:131], v[0:15]
	s_cbranch_vccnz .Lfd1_1754
	s_waitcnt vmcnt(15)
	ds_write_b128 v158, v[116:119] offset:4608
	s_waitcnt vmcnt(14)
	ds_write_b128 v158, v[84:87] offset:41472

.Lfd1_1756:
	s_waitcnt lgkmcnt(1)
	v_mfma_f32_32x32x16_bf16 v[48:63], v[144:147], v[148:151], v[48:63]
	s_and_b64 vcc, exec, s[6:7]
	s_waitcnt lgkmcnt(0)
	v_mfma_f32_32x32x16_bf16 v[32:47], v[144:147], v[140:143], v[32:47]
	v_mfma_f32_32x32x16_bf16 v[16:31], v[136:139], v[148:151], v[16:31]
	ds_read_b128 v[144:147], v160 offset:18528
	ds_read_b128 v[128:131], v160 offset:23136
	ds_read_b128 v[148:151], v159 offset:55392
	ds_read_b128 v[132:135], v159 offset:60000
	v_mfma_f32_32x32x16_bf16 v[0:15], v[136:139], v[140:143], v[0:15]
	s_cbranch_vccnz .Lfd1_1758
	s_waitcnt vmcnt(15)
	ds_write_b128 v158, v[120:123] offset:9216
	s_waitcnt vmcnt(14)
	ds_write_b128 v158, v[92:95] offset:46080

.Lfd1_1760:
	s_waitcnt lgkmcnt(1)
	v_mfma_f32_32x32x16_bf16 v[48:63], v[144:147], v[148:151], v[48:63]
	s_and_b64 vcc, exec, s[6:7]
	s_waitcnt lgkmcnt(0)
	v_mfma_f32_32x32x16_bf16 v[32:47], v[144:147], v[132:135], v[32:47]
	v_mfma_f32_32x32x16_bf16 v[16:31], v[128:131], v[148:151], v[16:31]
	v_mfma_f32_32x32x16_bf16 v[0:15], v[128:131], v[132:135], v[0:15]
	s_cbranch_vccnz .Lfd1_1762
	s_waitcnt vmcnt(15)
	ds_write_b128 v158, v[124:127] offset:13824
	s_waitcnt vmcnt(14)
	ds_write_b128 v158, v[108:111] offset:50688

; template <class AL, class BL>
; DI void gemm_core(AL al, BL bl, int m0, int n0, int K, char* smem, f32x16 (&acc)[2][2]) {
;     ...
;   for (int kt = 0; kt < nk; kt += 2) {
;     G_TILE(0, x, true, (kt + 3 < nk), kt + 3);
;     __syncthreads();
;     G_TILE(1, y, (kt + 2 < nk), (kt + 4 < nk), kt + 4);
;     __syncthreads();
;   }
.Lfd1_latch:
	s_add_i32 s1, s1, 2
	v_lshl_add_u64 v[164:165], v[164:165], 0, s[28:29]
	v_lshl_add_u64 v[162:163], v[162:163], 0, s[28:29]
	v_lshl_add_u64 v[166:167], v[166:167], 0, s[28:29]
	v_lshl_add_u64 v[168:169], v[168:169], 0, s[28:29]
	v_lshl_add_u64 v[170:171], v[170:171], 0, s[28:29]
	v_lshl_add_u64 v[172:173], v[172:173], 0, s[28:29]
	v_lshl_add_u64 v[174:175], v[174:175], 0, s[28:29]
	s_andn2_b64 vcc, exec, s[2:3]
	v_lshl_add_u64 v[176:177], v[176:177], 0, s[28:29]
	s_waitcnt lgkmcnt(0)
	s_barrier
	s_cbranch_vccz .LBB0_1730
	s_cmp_lt_u32 s1, 59
	s_cbranch_scc1 .Lfd1_hdr
	s_branch .LBB0_1740
